# P0 ABt fold item rewritten on the f32 matrix core (v_mfma_f32_16x16x4_f32, k-ordered f32 fma chain, bit-identical): each wave reads 32 KB of w_fourier instead of 256 KB
# speedup vs baseline: 1.0236x; 1.0104x over previous
.LBB0_69:
	v_and_b32_e32 v200, 15, v118
	v_lshrrev_b32_e32 v201, 4, v118
	v_readfirstlane_b32 s0, v2
	v_readfirstlane_b32 s1, v3
	v_lshlrev_b32_e32 v202, 10, v201
	v_lshl_add_u32 v202, v15, 7, v202
	v_lshl_add_u32 v202, v200, 3, v202
	s_lshl_b32 s7, s22, 3
	s_and_b32 s7, s7, 0xf8
	v_add_u32_e32 v203, s7, v200
	v_lshlrev_b32_e32 v204, 4, v203
	v_mul_u32_u24_e32 v205, v201, v203
	v_lshlrev_b32_e32 v205, 2, v205
	v_and_b32_e32 v205, 0x3fc, v205
	v_mov_b32_e32 v206, 0
	v_mov_b32_e32 v207, 0
	v_mov_b32_e32 v208, 0
	v_mov_b32_e32 v209, 0
	v_mov_b32_e32 v210, 0
	v_mov_b32_e32 v211, 0
	v_mov_b32_e32 v212, 0
	v_mov_b32_e32 v213, 0
	global_load_dwordx2 v[166:167], v202, s[0:1]
	ds_read_b32 v216, v205
	v_add_u32_e32 v205, v205, v204
	v_and_b32_e32 v205, 0x3fc, v205
	s_add_u32 s0, s0, 0x1000
	s_addc_u32 s1, s1, 0
	global_load_dwordx2 v[168:169], v202, s[0:1]
	ds_read_b32 v217, v205
	v_add_u32_e32 v205, v205, v204
	v_and_b32_e32 v205, 0x3fc, v205
	s_add_u32 s0, s0, 0x1000
	s_addc_u32 s1, s1, 0
	global_load_dwordx2 v[170:171], v202, s[0:1]
	ds_read_b32 v218, v205
	v_add_u32_e32 v205, v205, v204
	v_and_b32_e32 v205, 0x3fc, v205
	s_add_u32 s0, s0, 0x1000
	s_addc_u32 s1, s1, 0
	global_load_dwordx2 v[172:173], v202, s[0:1]
	ds_read_b32 v219, v205
	v_add_u32_e32 v205, v205, v204
	v_and_b32_e32 v205, 0x3fc, v205
	s_add_u32 s0, s0, 0x1000
	s_addc_u32 s1, s1, 0
	global_load_dwordx2 v[174:175], v202, s[0:1]
	ds_read_b32 v220, v205
	v_add_u32_e32 v205, v205, v204
	v_and_b32_e32 v205, 0x3fc, v205
	s_add_u32 s0, s0, 0x1000
	s_addc_u32 s1, s1, 0
	global_load_dwordx2 v[176:177], v202, s[0:1]
	ds_read_b32 v221, v205
	v_add_u32_e32 v205, v205, v204
	v_and_b32_e32 v205, 0x3fc, v205
	s_add_u32 s0, s0, 0x1000
	s_addc_u32 s1, s1, 0
	global_load_dwordx2 v[178:179], v202, s[0:1]
	ds_read_b32 v222, v205
	v_add_u32_e32 v205, v205, v204
	v_and_b32_e32 v205, 0x3fc, v205
	s_add_u32 s0, s0, 0x1000
	s_addc_u32 s1, s1, 0
	global_load_dwordx2 v[180:181], v202, s[0:1]
	ds_read_b32 v223, v205
	v_add_u32_e32 v205, v205, v204
	v_and_b32_e32 v205, 0x3fc, v205
	s_add_u32 s0, s0, 0x1000
	s_addc_u32 s1, s1, 0
	global_load_dwordx2 v[182:183], v202, s[0:1]
	ds_read_b32 v224, v205
	v_add_u32_e32 v205, v205, v204
	v_and_b32_e32 v205, 0x3fc, v205
	s_add_u32 s0, s0, 0x1000
	s_addc_u32 s1, s1, 0
	global_load_dwordx2 v[184:185], v202, s[0:1]
	ds_read_b32 v225, v205
	v_add_u32_e32 v205, v205, v204
	v_and_b32_e32 v205, 0x3fc, v205
	s_add_u32 s0, s0, 0x1000
	s_addc_u32 s1, s1, 0
	global_load_dwordx2 v[186:187], v202, s[0:1]
	ds_read_b32 v226, v205
	v_add_u32_e32 v205, v205, v204
	v_and_b32_e32 v205, 0x3fc, v205
	s_add_u32 s0, s0, 0x1000
	s_addc_u32 s1, s1, 0
	global_load_dwordx2 v[188:189], v202, s[0:1]
	ds_read_b32 v227, v205
	v_add_u32_e32 v205, v205, v204
	v_and_b32_e32 v205, 0x3fc, v205
	s_add_u32 s0, s0, 0x1000
	s_addc_u32 s1, s1, 0
	global_load_dwordx2 v[190:191], v202, s[0:1]
	ds_read_b32 v228, v205
	v_add_u32_e32 v205, v205, v204
	v_and_b32_e32 v205, 0x3fc, v205
	s_add_u32 s0, s0, 0x1000
	s_addc_u32 s1, s1, 0
	global_load_dwordx2 v[192:193], v202, s[0:1]
	ds_read_b32 v229, v205
	v_add_u32_e32 v205, v205, v204
	v_and_b32_e32 v205, 0x3fc, v205
	s_add_u32 s0, s0, 0x1000
	s_addc_u32 s1, s1, 0
	global_load_dwordx2 v[194:195], v202, s[0:1]
	ds_read_b32 v230, v205
	v_add_u32_e32 v205, v205, v204
	v_and_b32_e32 v205, 0x3fc, v205
	s_add_u32 s0, s0, 0x1000
	s_addc_u32 s1, s1, 0
	global_load_dwordx2 v[196:197], v202, s[0:1]
	ds_read_b32 v231, v205
	v_add_u32_e32 v205, v205, v204
	v_and_b32_e32 v205, 0x3fc, v205
	s_waitcnt vmcnt(15) lgkmcnt(15)
	v_mfma_f32_16x16x4_f32 v[206:209], v166, v216, v[206:209]
	v_mfma_f32_16x16x4_f32 v[210:213], v167, v216, v[210:213]
	s_add_u32 s0, s0, 0x1000
	s_addc_u32 s1, s1, 0
	global_load_dwordx2 v[166:167], v202, s[0:1]
	ds_read_b32 v216, v205
	v_add_u32_e32 v205, v205, v204
	v_and_b32_e32 v205, 0x3fc, v205
	s_waitcnt vmcnt(15) lgkmcnt(15)
	v_mfma_f32_16x16x4_f32 v[206:209], v168, v217, v[206:209]
	v_mfma_f32_16x16x4_f32 v[210:213], v169, v217, v[210:213]
	s_add_u32 s0, s0, 0x1000
	s_addc_u32 s1, s1, 0
	global_load_dwordx2 v[168:169], v202, s[0:1]
	ds_read_b32 v217, v205
	v_add_u32_e32 v205, v205, v204
	v_and_b32_e32 v205, 0x3fc, v205
	s_waitcnt vmcnt(15) lgkmcnt(15)
	v_mfma_f32_16x16x4_f32 v[206:209], v170, v218, v[206:209]
	v_mfma_f32_16x16x4_f32 v[210:213], v171, v218, v[210:213]
	s_add_u32 s0, s0, 0x1000
	s_addc_u32 s1, s1, 0
	global_load_dwordx2 v[170:171], v202, s[0:1]
	ds_read_b32 v218, v205
	v_add_u32_e32 v205, v205, v204
	v_and_b32_e32 v205, 0x3fc, v205
	s_waitcnt vmcnt(15) lgkmcnt(15)
	v_mfma_f32_16x16x4_f32 v[206:209], v172, v219, v[206:209]
	v_mfma_f32_16x16x4_f32 v[210:213], v173, v219, v[210:213]
	s_add_u32 s0, s0, 0x1000
	s_addc_u32 s1, s1, 0
	global_load_dwordx2 v[172:173], v202, s[0:1]
	ds_read_b32 v219, v205
	v_add_u32_e32 v205, v205, v204
	v_and_b32_e32 v205, 0x3fc, v205
	s_waitcnt vmcnt(15) lgkmcnt(15)
	v_mfma_f32_16x16x4_f32 v[206:209], v174, v220, v[206:209]
	v_mfma_f32_16x16x4_f32 v[210:213], v175, v220, v[210:213]
	s_add_u32 s0, s0, 0x1000
	s_addc_u32 s1, s1, 0
	global_load_dwordx2 v[174:175], v202, s[0:1]
	ds_read_b32 v220, v205
	v_add_u32_e32 v205, v205, v204
	v_and_b32_e32 v205, 0x3fc, v205
	s_waitcnt vmcnt(15) lgkmcnt(15)
	v_mfma_f32_16x16x4_f32 v[206:209], v176, v221, v[206:209]
	v_mfma_f32_16x16x4_f32 v[210:213], v177, v221, v[210:213]
	s_add_u32 s0, s0, 0x1000
	s_addc_u32 s1, s1, 0
	global_load_dwordx2 v[176:177], v202, s[0:1]
	ds_read_b32 v221, v205
	v_add_u32_e32 v205, v205, v204
	v_and_b32_e32 v205, 0x3fc, v205
	s_waitcnt vmcnt(15) lgkmcnt(15)
	v_mfma_f32_16x16x4_f32 v[206:209], v178, v222, v[206:209]
	v_mfma_f32_16x16x4_f32 v[210:213], v179, v222, v[210:213]
	s_add_u32 s0, s0, 0x1000
	s_addc_u32 s1, s1, 0
	global_load_dwordx2 v[178:179], v202, s[0:1]
	ds_read_b32 v222, v205
	v_add_u32_e32 v205, v205, v204
	v_and_b32_e32 v205, 0x3fc, v205
	s_waitcnt vmcnt(15) lgkmcnt(15)
	v_mfma_f32_16x16x4_f32 v[206:209], v180, v223, v[206:209]
	v_mfma_f32_16x16x4_f32 v[210:213], v181, v223, v[210:213]
	s_add_u32 s0, s0, 0x1000
	s_addc_u32 s1, s1, 0
	global_load_dwordx2 v[180:181], v202, s[0:1]
	ds_read_b32 v223, v205
	v_add_u32_e32 v205, v205, v204
	v_and_b32_e32 v205, 0x3fc, v205
	s_waitcnt vmcnt(15) lgkmcnt(15)
	v_mfma_f32_16x16x4_f32 v[206:209], v182, v224, v[206:209]
	v_mfma_f32_16x16x4_f32 v[210:213], v183, v224, v[210:213]
	s_add_u32 s0, s0, 0x1000
	s_addc_u32 s1, s1, 0
	global_load_dwordx2 v[182:183], v202, s[0:1]
	ds_read_b32 v224, v205
	v_add_u32_e32 v205, v205, v204
	v_and_b32_e32 v205, 0x3fc, v205
	s_waitcnt vmcnt(15) lgkmcnt(15)
	v_mfma_f32_16x16x4_f32 v[206:209], v184, v225, v[206:209]
	v_mfma_f32_16x16x4_f32 v[210:213], v185, v225, v[210:213]
	s_add_u32 s0, s0, 0x1000
	s_addc_u32 s1, s1, 0
	global_load_dwordx2 v[184:185], v202, s[0:1]
	ds_read_b32 v225, v205
	v_add_u32_e32 v205, v205, v204
	v_and_b32_e32 v205, 0x3fc, v205
	s_waitcnt vmcnt(15) lgkmcnt(15)
	v_mfma_f32_16x16x4_f32 v[206:209], v186, v226, v[206:209]
	v_mfma_f32_16x16x4_f32 v[210:213], v187, v226, v[210:213]
	s_add_u32 s0, s0, 0x1000
	s_addc_u32 s1, s1, 0
	global_load_dwordx2 v[186:187], v202, s[0:1]
	ds_read_b32 v226, v205
	v_add_u32_e32 v205, v205, v204
	v_and_b32_e32 v205, 0x3fc, v205
	s_waitcnt vmcnt(15) lgkmcnt(15)
	v_mfma_f32_16x16x4_f32 v[206:209], v188, v227, v[206:209]
	v_mfma_f32_16x16x4_f32 v[210:213], v189, v227, v[210:213]
	s_add_u32 s0, s0, 0x1000
	s_addc_u32 s1, s1, 0
	global_load_dwordx2 v[188:189], v202, s[0:1]
	ds_read_b32 v227, v205
	v_add_u32_e32 v205, v205, v204
	v_and_b32_e32 v205, 0x3fc, v205
	s_waitcnt vmcnt(15) lgkmcnt(15)
	v_mfma_f32_16x16x4_f32 v[206:209], v190, v228, v[206:209]
	v_mfma_f32_16x16x4_f32 v[210:213], v191, v228, v[210:213]
	s_add_u32 s0, s0, 0x1000
	s_addc_u32 s1, s1, 0
	global_load_dwordx2 v[190:191], v202, s[0:1]
	ds_read_b32 v228, v205
	v_add_u32_e32 v205, v205, v204
	v_and_b32_e32 v205, 0x3fc, v205
	s_waitcnt vmcnt(15) lgkmcnt(15)
	v_mfma_f32_16x16x4_f32 v[206:209], v192, v229, v[206:209]
	v_mfma_f32_16x16x4_f32 v[210:213], v193, v229, v[210:213]
	s_add_u32 s0, s0, 0x1000
	s_addc_u32 s1, s1, 0
	global_load_dwordx2 v[192:193], v202, s[0:1]
	ds_read_b32 v229, v205
	v_add_u32_e32 v205, v205, v204
	v_and_b32_e32 v205, 0x3fc, v205
	s_waitcnt vmcnt(15) lgkmcnt(15)
	v_mfma_f32_16x16x4_f32 v[206:209], v194, v230, v[206:209]
	v_mfma_f32_16x16x4_f32 v[210:213], v195, v230, v[210:213]
	s_add_u32 s0, s0, 0x1000
	s_addc_u32 s1, s1, 0
	global_load_dwordx2 v[194:195], v202, s[0:1]
	ds_read_b32 v230, v205
	v_add_u32_e32 v205, v205, v204
	v_and_b32_e32 v205, 0x3fc, v205
	s_waitcnt vmcnt(15) lgkmcnt(15)
	v_mfma_f32_16x16x4_f32 v[206:209], v196, v231, v[206:209]
	v_mfma_f32_16x16x4_f32 v[210:213], v197, v231, v[210:213]
	s_add_u32 s0, s0, 0x1000
	s_addc_u32 s1, s1, 0
	global_load_dwordx2 v[196:197], v202, s[0:1]
	ds_read_b32 v231, v205
	v_add_u32_e32 v205, v205, v204
	v_and_b32_e32 v205, 0x3fc, v205
	s_waitcnt vmcnt(15) lgkmcnt(15)
	v_mfma_f32_16x16x4_f32 v[206:209], v166, v216, v[206:209]
	v_mfma_f32_16x16x4_f32 v[210:213], v167, v216, v[210:213]
	s_add_u32 s0, s0, 0x1000
	s_addc_u32 s1, s1, 0
	global_load_dwordx2 v[166:167], v202, s[0:1]
	ds_read_b32 v216, v205
	v_add_u32_e32 v205, v205, v204
	v_and_b32_e32 v205, 0x3fc, v205
	s_waitcnt vmcnt(15) lgkmcnt(15)
	v_mfma_f32_16x16x4_f32 v[206:209], v168, v217, v[206:209]
	v_mfma_f32_16x16x4_f32 v[210:213], v169, v217, v[210:213]
	s_add_u32 s0, s0, 0x1000
	s_addc_u32 s1, s1, 0
	global_load_dwordx2 v[168:169], v202, s[0:1]
	ds_read_b32 v217, v205
	v_add_u32_e32 v205, v205, v204
	v_and_b32_e32 v205, 0x3fc, v205
	s_waitcnt vmcnt(15) lgkmcnt(15)
	v_mfma_f32_16x16x4_f32 v[206:209], v170, v218, v[206:209]
	v_mfma_f32_16x16x4_f32 v[210:213], v171, v218, v[210:213]
	s_add_u32 s0, s0, 0x1000
	s_addc_u32 s1, s1, 0
	global_load_dwordx2 v[170:171], v202, s[0:1]
	ds_read_b32 v218, v205
	v_add_u32_e32 v205, v205, v204
	v_and_b32_e32 v205, 0x3fc, v205
	s_waitcnt vmcnt(15) lgkmcnt(15)
	v_mfma_f32_16x16x4_f32 v[206:209], v172, v219, v[206:209]
	v_mfma_f32_16x16x4_f32 v[210:213], v173, v219, v[210:213]
	s_add_u32 s0, s0, 0x1000
	s_addc_u32 s1, s1, 0
	global_load_dwordx2 v[172:173], v202, s[0:1]
	ds_read_b32 v219, v205
	v_add_u32_e32 v205, v205, v204
	v_and_b32_e32 v205, 0x3fc, v205
	s_waitcnt vmcnt(15) lgkmcnt(15)
	v_mfma_f32_16x16x4_f32 v[206:209], v174, v220, v[206:209]
	v_mfma_f32_16x16x4_f32 v[210:213], v175, v220, v[210:213]
	s_add_u32 s0, s0, 0x1000
	s_addc_u32 s1, s1, 0
	global_load_dwordx2 v[174:175], v202, s[0:1]
	ds_read_b32 v220, v205
	v_add_u32_e32 v205, v205, v204
	v_and_b32_e32 v205, 0x3fc, v205
	s_waitcnt vmcnt(15) lgkmcnt(15)
	v_mfma_f32_16x16x4_f32 v[206:209], v176, v221, v[206:209]
	v_mfma_f32_16x16x4_f32 v[210:213], v177, v221, v[210:213]
	s_add_u32 s0, s0, 0x1000
	s_addc_u32 s1, s1, 0
	global_load_dwordx2 v[176:177], v202, s[0:1]
	ds_read_b32 v221, v205
	v_add_u32_e32 v205, v205, v204
	v_and_b32_e32 v205, 0x3fc, v205
	s_waitcnt vmcnt(15) lgkmcnt(15)
	v_mfma_f32_16x16x4_f32 v[206:209], v178, v222, v[206:209]
	v_mfma_f32_16x16x4_f32 v[210:213], v179, v222, v[210:213]
	s_add_u32 s0, s0, 0x1000
	s_addc_u32 s1, s1, 0
	global_load_dwordx2 v[178:179], v202, s[0:1]
	ds_read_b32 v222, v205
	v_add_u32_e32 v205, v205, v204
	v_and_b32_e32 v205, 0x3fc, v205
	s_waitcnt vmcnt(15) lgkmcnt(15)
	v_mfma_f32_16x16x4_f32 v[206:209], v180, v223, v[206:209]
	v_mfma_f32_16x16x4_f32 v[210:213], v181, v223, v[210:213]
	s_add_u32 s0, s0, 0x1000
	s_addc_u32 s1, s1, 0
	global_load_dwordx2 v[180:181], v202, s[0:1]
	ds_read_b32 v223, v205
	v_add_u32_e32 v205, v205, v204
	v_and_b32_e32 v205, 0x3fc, v205
	s_waitcnt vmcnt(15) lgkmcnt(15)
	v_mfma_f32_16x16x4_f32 v[206:209], v182, v224, v[206:209]
	v_mfma_f32_16x16x4_f32 v[210:213], v183, v224, v[210:213]
	s_add_u32 s0, s0, 0x1000
	s_addc_u32 s1, s1, 0
	global_load_dwordx2 v[182:183], v202, s[0:1]
	ds_read_b32 v224, v205
	v_add_u32_e32 v205, v205, v204
	v_and_b32_e32 v205, 0x3fc, v205
	s_waitcnt vmcnt(15) lgkmcnt(15)
	v_mfma_f32_16x16x4_f32 v[206:209], v184, v225, v[206:209]
	v_mfma_f32_16x16x4_f32 v[210:213], v185, v225, v[210:213]
	s_add_u32 s0, s0, 0x1000
	s_addc_u32 s1, s1, 0
	global_load_dwordx2 v[184:185], v202, s[0:1]
	ds_read_b32 v225, v205
	v_add_u32_e32 v205, v205, v204
	v_and_b32_e32 v205, 0x3fc, v205
	s_waitcnt vmcnt(15) lgkmcnt(15)
	v_mfma_f32_16x16x4_f32 v[206:209], v186, v226, v[206:209]
	v_mfma_f32_16x16x4_f32 v[210:213], v187, v226, v[210:213]
	s_add_u32 s0, s0, 0x1000
	s_addc_u32 s1, s1, 0
	global_load_dwordx2 v[186:187], v202, s[0:1]
	ds_read_b32 v226, v205
	v_add_u32_e32 v205, v205, v204
	v_and_b32_e32 v205, 0x3fc, v205
	s_waitcnt vmcnt(15) lgkmcnt(15)
	v_mfma_f32_16x16x4_f32 v[206:209], v188, v227, v[206:209]
	v_mfma_f32_16x16x4_f32 v[210:213], v189, v227, v[210:213]
	s_add_u32 s0, s0, 0x1000
	s_addc_u32 s1, s1, 0
	global_load_dwordx2 v[188:189], v202, s[0:1]
	ds_read_b32 v227, v205
	v_add_u32_e32 v205, v205, v204
	v_and_b32_e32 v205, 0x3fc, v205
	s_waitcnt vmcnt(15) lgkmcnt(15)
	v_mfma_f32_16x16x4_f32 v[206:209], v190, v228, v[206:209]
	v_mfma_f32_16x16x4_f32 v[210:213], v191, v228, v[210:213]
	s_add_u32 s0, s0, 0x1000
	s_addc_u32 s1, s1, 0
	global_load_dwordx2 v[190:191], v202, s[0:1]
	ds_read_b32 v228, v205
	v_add_u32_e32 v205, v205, v204
	v_and_b32_e32 v205, 0x3fc, v205
	s_waitcnt vmcnt(15) lgkmcnt(15)
	v_mfma_f32_16x16x4_f32 v[206:209], v192, v229, v[206:209]
	v_mfma_f32_16x16x4_f32 v[210:213], v193, v229, v[210:213]
	s_add_u32 s0, s0, 0x1000
	s_addc_u32 s1, s1, 0
	global_load_dwordx2 v[192:193], v202, s[0:1]
	ds_read_b32 v229, v205
	v_add_u32_e32 v205, v205, v204
	v_and_b32_e32 v205, 0x3fc, v205
	s_waitcnt vmcnt(15) lgkmcnt(15)
	v_mfma_f32_16x16x4_f32 v[206:209], v194, v230, v[206:209]
	v_mfma_f32_16x16x4_f32 v[210:213], v195, v230, v[210:213]
	s_add_u32 s0, s0, 0x1000
	s_addc_u32 s1, s1, 0
	global_load_dwordx2 v[194:195], v202, s[0:1]
	ds_read_b32 v230, v205
	v_add_u32_e32 v205, v205, v204
	v_and_b32_e32 v205, 0x3fc, v205
	s_waitcnt vmcnt(15) lgkmcnt(15)
	v_mfma_f32_16x16x4_f32 v[206:209], v196, v231, v[206:209]
	v_mfma_f32_16x16x4_f32 v[210:213], v197, v231, v[210:213]
	s_add_u32 s0, s0, 0x1000
	s_addc_u32 s1, s1, 0
	global_load_dwordx2 v[196:197], v202, s[0:1]
	ds_read_b32 v231, v205
	v_add_u32_e32 v205, v205, v204
	v_and_b32_e32 v205, 0x3fc, v205
	s_waitcnt vmcnt(15) lgkmcnt(15)
	v_mfma_f32_16x16x4_f32 v[206:209], v166, v216, v[206:209]
	v_mfma_f32_16x16x4_f32 v[210:213], v167, v216, v[210:213]
	s_add_u32 s0, s0, 0x1000
	s_addc_u32 s1, s1, 0
	global_load_dwordx2 v[166:167], v202, s[0:1]
	ds_read_b32 v216, v205
	v_add_u32_e32 v205, v205, v204
	v_and_b32_e32 v205, 0x3fc, v205
	s_waitcnt vmcnt(15) lgkmcnt(15)
	v_mfma_f32_16x16x4_f32 v[206:209], v168, v217, v[206:209]
	v_mfma_f32_16x16x4_f32 v[210:213], v169, v217, v[210:213]
	s_add_u32 s0, s0, 0x1000
	s_addc_u32 s1, s1, 0
	global_load_dwordx2 v[168:169], v202, s[0:1]
	ds_read_b32 v217, v205
	v_add_u32_e32 v205, v205, v204
	v_and_b32_e32 v205, 0x3fc, v205
	s_waitcnt vmcnt(15) lgkmcnt(15)
	v_mfma_f32_16x16x4_f32 v[206:209], v170, v218, v[206:209]
	v_mfma_f32_16x16x4_f32 v[210:213], v171, v218, v[210:213]
	s_add_u32 s0, s0, 0x1000
	s_addc_u32 s1, s1, 0
	global_load_dwordx2 v[170:171], v202, s[0:1]
	ds_read_b32 v218, v205
	v_add_u32_e32 v205, v205, v204
	v_and_b32_e32 v205, 0x3fc, v205
	s_waitcnt vmcnt(15) lgkmcnt(15)
	v_mfma_f32_16x16x4_f32 v[206:209], v172, v219, v[206:209]
	v_mfma_f32_16x16x4_f32 v[210:213], v173, v219, v[210:213]
	s_add_u32 s0, s0, 0x1000
	s_addc_u32 s1, s1, 0
	global_load_dwordx2 v[172:173], v202, s[0:1]
	ds_read_b32 v219, v205
	v_add_u32_e32 v205, v205, v204
	v_and_b32_e32 v205, 0x3fc, v205
	s_waitcnt vmcnt(15) lgkmcnt(15)
	v_mfma_f32_16x16x4_f32 v[206:209], v174, v220, v[206:209]
	v_mfma_f32_16x16x4_f32 v[210:213], v175, v220, v[210:213]
	s_add_u32 s0, s0, 0x1000
	s_addc_u32 s1, s1, 0
	global_load_dwordx2 v[174:175], v202, s[0:1]
	ds_read_b32 v220, v205
	v_add_u32_e32 v205, v205, v204
	v_and_b32_e32 v205, 0x3fc, v205
	s_waitcnt vmcnt(15) lgkmcnt(15)
	v_mfma_f32_16x16x4_f32 v[206:209], v176, v221, v[206:209]
	v_mfma_f32_16x16x4_f32 v[210:213], v177, v221, v[210:213]
	s_add_u32 s0, s0, 0x1000
	s_addc_u32 s1, s1, 0
	global_load_dwordx2 v[176:177], v202, s[0:1]
	ds_read_b32 v221, v205
	v_add_u32_e32 v205, v205, v204
	v_and_b32_e32 v205, 0x3fc, v205
	s_waitcnt vmcnt(15) lgkmcnt(15)
	v_mfma_f32_16x16x4_f32 v[206:209], v178, v222, v[206:209]
	v_mfma_f32_16x16x4_f32 v[210:213], v179, v222, v[210:213]
	s_add_u32 s0, s0, 0x1000
	s_addc_u32 s1, s1, 0
	global_load_dwordx2 v[178:179], v202, s[0:1]
	ds_read_b32 v222, v205
	v_add_u32_e32 v205, v205, v204
	v_and_b32_e32 v205, 0x3fc, v205
	s_waitcnt vmcnt(15) lgkmcnt(15)
	v_mfma_f32_16x16x4_f32 v[206:209], v180, v223, v[206:209]
	v_mfma_f32_16x16x4_f32 v[210:213], v181, v223, v[210:213]
	s_add_u32 s0, s0, 0x1000
	s_addc_u32 s1, s1, 0
	global_load_dwordx2 v[180:181], v202, s[0:1]
	ds_read_b32 v223, v205
	v_add_u32_e32 v205, v205, v204
	v_and_b32_e32 v205, 0x3fc, v205
	s_waitcnt vmcnt(15) lgkmcnt(15)
	v_mfma_f32_16x16x4_f32 v[206:209], v182, v224, v[206:209]
	v_mfma_f32_16x16x4_f32 v[210:213], v183, v224, v[210:213]
	s_add_u32 s0, s0, 0x1000
	s_addc_u32 s1, s1, 0
	global_load_dwordx2 v[182:183], v202, s[0:1]
	ds_read_b32 v224, v205
	v_add_u32_e32 v205, v205, v204
	v_and_b32_e32 v205, 0x3fc, v205
	s_waitcnt vmcnt(15) lgkmcnt(15)
	v_mfma_f32_16x16x4_f32 v[206:209], v184, v225, v[206:209]
	v_mfma_f32_16x16x4_f32 v[210:213], v185, v225, v[210:213]
	s_add_u32 s0, s0, 0x1000
	s_addc_u32 s1, s1, 0
	global_load_dwordx2 v[184:185], v202, s[0:1]
	ds_read_b32 v225, v205
	v_add_u32_e32 v205, v205, v204
	v_and_b32_e32 v205, 0x3fc, v205
	s_waitcnt vmcnt(15) lgkmcnt(15)
	v_mfma_f32_16x16x4_f32 v[206:209], v186, v226, v[206:209]
	v_mfma_f32_16x16x4_f32 v[210:213], v187, v226, v[210:213]
	s_add_u32 s0, s0, 0x1000
	s_addc_u32 s1, s1, 0
	global_load_dwordx2 v[186:187], v202, s[0:1]
	ds_read_b32 v226, v205
	v_add_u32_e32 v205, v205, v204
	v_and_b32_e32 v205, 0x3fc, v205
	s_waitcnt vmcnt(15) lgkmcnt(15)
	v_mfma_f32_16x16x4_f32 v[206:209], v188, v227, v[206:209]
	v_mfma_f32_16x16x4_f32 v[210:213], v189, v227, v[210:213]
	s_add_u32 s0, s0, 0x1000
	s_addc_u32 s1, s1, 0
	global_load_dwordx2 v[188:189], v202, s[0:1]
	ds_read_b32 v227, v205
	v_add_u32_e32 v205, v205, v204
	v_and_b32_e32 v205, 0x3fc, v205
	s_waitcnt vmcnt(15) lgkmcnt(15)
	v_mfma_f32_16x16x4_f32 v[206:209], v190, v228, v[206:209]
	v_mfma_f32_16x16x4_f32 v[210:213], v191, v228, v[210:213]
	s_add_u32 s0, s0, 0x1000
	s_addc_u32 s1, s1, 0
	global_load_dwordx2 v[190:191], v202, s[0:1]
	ds_read_b32 v228, v205
	v_add_u32_e32 v205, v205, v204
	v_and_b32_e32 v205, 0x3fc, v205
	s_waitcnt vmcnt(15) lgkmcnt(15)
	v_mfma_f32_16x16x4_f32 v[206:209], v192, v229, v[206:209]
	v_mfma_f32_16x16x4_f32 v[210:213], v193, v229, v[210:213]
	s_add_u32 s0, s0, 0x1000
	s_addc_u32 s1, s1, 0
	global_load_dwordx2 v[192:193], v202, s[0:1]
	ds_read_b32 v229, v205
	v_add_u32_e32 v205, v205, v204
	v_and_b32_e32 v205, 0x3fc, v205
	s_waitcnt vmcnt(15) lgkmcnt(15)
	v_mfma_f32_16x16x4_f32 v[206:209], v194, v230, v[206:209]
	v_mfma_f32_16x16x4_f32 v[210:213], v195, v230, v[210:213]
	s_add_u32 s0, s0, 0x1000
	s_addc_u32 s1, s1, 0
	global_load_dwordx2 v[194:195], v202, s[0:1]
	ds_read_b32 v230, v205
	v_add_u32_e32 v205, v205, v204
	v_and_b32_e32 v205, 0x3fc, v205
	s_waitcnt vmcnt(15) lgkmcnt(15)
	v_mfma_f32_16x16x4_f32 v[206:209], v196, v231, v[206:209]
	v_mfma_f32_16x16x4_f32 v[210:213], v197, v231, v[210:213]
	s_add_u32 s0, s0, 0x1000
	s_addc_u32 s1, s1, 0
	global_load_dwordx2 v[196:197], v202, s[0:1]
	ds_read_b32 v231, v205
	s_waitcnt vmcnt(15) lgkmcnt(15)
	v_mfma_f32_16x16x4_f32 v[206:209], v166, v216, v[206:209]
	v_mfma_f32_16x16x4_f32 v[210:213], v167, v216, v[210:213]
	s_waitcnt vmcnt(14) lgkmcnt(14)
	v_mfma_f32_16x16x4_f32 v[206:209], v168, v217, v[206:209]
	v_mfma_f32_16x16x4_f32 v[210:213], v169, v217, v[210:213]
	s_waitcnt vmcnt(13) lgkmcnt(13)
	v_mfma_f32_16x16x4_f32 v[206:209], v170, v218, v[206:209]
	v_mfma_f32_16x16x4_f32 v[210:213], v171, v218, v[210:213]
	s_waitcnt vmcnt(12) lgkmcnt(12)
	v_mfma_f32_16x16x4_f32 v[206:209], v172, v219, v[206:209]
	v_mfma_f32_16x16x4_f32 v[210:213], v173, v219, v[210:213]
	s_waitcnt vmcnt(11) lgkmcnt(11)
	v_mfma_f32_16x16x4_f32 v[206:209], v174, v220, v[206:209]
	v_mfma_f32_16x16x4_f32 v[210:213], v175, v220, v[210:213]
	s_waitcnt vmcnt(10) lgkmcnt(10)
	v_mfma_f32_16x16x4_f32 v[206:209], v176, v221, v[206:209]
	v_mfma_f32_16x16x4_f32 v[210:213], v177, v221, v[210:213]
	s_waitcnt vmcnt(9) lgkmcnt(9)
	v_mfma_f32_16x16x4_f32 v[206:209], v178, v222, v[206:209]
	v_mfma_f32_16x16x4_f32 v[210:213], v179, v222, v[210:213]
	s_waitcnt vmcnt(8) lgkmcnt(8)
	v_mfma_f32_16x16x4_f32 v[206:209], v180, v223, v[206:209]
	v_mfma_f32_16x16x4_f32 v[210:213], v181, v223, v[210:213]
	s_waitcnt vmcnt(7) lgkmcnt(7)
	v_mfma_f32_16x16x4_f32 v[206:209], v182, v224, v[206:209]
	v_mfma_f32_16x16x4_f32 v[210:213], v183, v224, v[210:213]
	s_waitcnt vmcnt(6) lgkmcnt(6)
	v_mfma_f32_16x16x4_f32 v[206:209], v184, v225, v[206:209]
	v_mfma_f32_16x16x4_f32 v[210:213], v185, v225, v[210:213]
	s_waitcnt vmcnt(5) lgkmcnt(5)
	v_mfma_f32_16x16x4_f32 v[206:209], v186, v226, v[206:209]
	v_mfma_f32_16x16x4_f32 v[210:213], v187, v226, v[210:213]
	s_waitcnt vmcnt(4) lgkmcnt(4)
	v_mfma_f32_16x16x4_f32 v[206:209], v188, v227, v[206:209]
	v_mfma_f32_16x16x4_f32 v[210:213], v189, v227, v[210:213]
	s_waitcnt vmcnt(3) lgkmcnt(3)
	v_mfma_f32_16x16x4_f32 v[206:209], v190, v228, v[206:209]
	v_mfma_f32_16x16x4_f32 v[210:213], v191, v228, v[210:213]
	s_waitcnt vmcnt(2) lgkmcnt(2)
	v_mfma_f32_16x16x4_f32 v[206:209], v192, v229, v[206:209]
	v_mfma_f32_16x16x4_f32 v[210:213], v193, v229, v[210:213]
	s_waitcnt vmcnt(1) lgkmcnt(1)
	v_mfma_f32_16x16x4_f32 v[206:209], v194, v230, v[206:209]
	v_mfma_f32_16x16x4_f32 v[210:213], v195, v230, v[210:213]
	s_waitcnt vmcnt(0) lgkmcnt(0)
	v_mfma_f32_16x16x4_f32 v[206:209], v196, v231, v[206:209]
	v_mfma_f32_16x16x4_f32 v[210:213], v197, v231, v[210:213]
	s_nop 15
	s_nop 3
	s_lshl_b32 s0, s22, 3
	s_addk_i32 s0, 0x8e00
	s_and_b32 s0, s0, 0xfffffe00
	s_lshl_b32 s1, s6, 8
	s_or_b32 s0, s0, s1
	v_lshl_add_u32 v232, v15, 5, s0
	v_lshl_add_u32 v232, v201, 3, v232
	v_mov_b32_e32 v233, 0
	v_lshlrev_b64 v[232:233], 9, v[232:233]
	v_lshl_add_u64 v[232:233], s[68:69], 0, v[232:233]
	v_lshlrev_b32_e32 v234, 1, v203
	v_mov_b32_e32 v235, 0
	v_lshl_add_u64 v[232:233], v[232:233], 0, v[234:235]
	v_cmp_gt_u32_e32 vcc, 8, v200
	s_and_saveexec_b64 s[0:1], vcc
	v_mul_f32_e32 v236, 0x3ab504f3, v206
	v_cvt_pk_bf16_f32 v236, v236, v7
	global_store_short v[232:233], v236, off
	v_mul_f32_e32 v236, 0x3ab504f3, v207
	v_cvt_pk_bf16_f32 v236, v236, v7
	global_store_short v[232:233], v236, off offset:1024
	v_mul_f32_e32 v236, 0x3ab504f3, v208
	v_cvt_pk_bf16_f32 v236, v236, v7
	global_store_short v[232:233], v236, off offset:2048
	v_mul_f32_e32 v236, 0x3ab504f3, v209
	v_cvt_pk_bf16_f32 v236, v236, v7
	global_store_short v[232:233], v236, off offset:3072
	v_mul_f32_e32 v236, 0x3ab504f3, v210
	v_cvt_pk_bf16_f32 v236, v236, v7
	global_store_short v[232:233], v236, off offset:512
	v_mul_f32_e32 v236, 0x3ab504f3, v211
	v_cvt_pk_bf16_f32 v236, v236, v7
	global_store_short v[232:233], v236, off offset:1536
	v_mul_f32_e32 v236, 0x3ab504f3, v212
	v_cvt_pk_bf16_f32 v236, v236, v7
	global_store_short v[232:233], v236, off offset:2560
	v_mul_f32_e32 v236, 0x3ab504f3, v213
	v_cvt_pk_bf16_f32 v236, v236, v7
	global_store_short v[232:233], v236, off offset:3584
	s_or_b64 exec, exec, s[0:1]
